# plus pipelined prep u/v conversion loop, peer_a next-token prefetch, gemm1 mainloop with 2-step DMA lead
# baseline (speedup 1.0000x reference)
; DI int otid() { int t; asm volatile("v_mov_b32 %0, %1" : "=v"(t) : "v"((int)threadIdx.x)); return t; }
; DI void convert_i8_job(const float* __restrict__ src, unsigned char* __restrict__ dst, int job, float scale) {
;   const int tid = otid();
; #pragma unroll
;   for (int i = 0; i < 2; ++i) {
;     size_t e = (size_t)job * 8192 + (size_t)(i * 256 + tid) * 16;
;     unsigned o[4];
; #pragma unroll
;     for (int q = 0; q < 4; ++q) {
;       float4 a = *(const float4*)(src + e + 4 * q);
;       o[q] = pack_i8x4(a.x, a.y, a.z, a.w, scale);
;     }
;     const size_t row = e >> 10; const int col = (int)(e & 1023);
;     *(uint4*)(dst + (size_t)(col >> 7) * ((size_t)NEXP * 128) + row * 128 + (col & 127)) = make_uint4(o[0], o[1], o[2], o[3]);
;   }
; }
; __device__ void phase_prep(const Params& p, int bid, int nb, char* lds) {
;     ...
;     j -= J_ADA;
;     if (j < J_TIN) { transpose_job(p.w_in, 2304, (bf16_t*)(p.ws + OFF_WIN), j / 36, j % 36, nullptr, nullptr, tile); continue; }
;     j -= J_TIN;
;     if (j < J_TOUT) { transpose_job(p.w_out, 1024, (bf16_t*)(p.ws + OFF_WOUT), j / 16, j % 16, p.gna, p.gnb, tile); continue; }
;     j -= J_TOUT;
;     if (j < J_TQ) { transpose_job(p.wq, 2048, (bf16_t*)(p.ws + OFF_WQ), j / 32, j % 32, nullptr, nullptr, tile); continue; }
;     j -= J_TQ;
;     if (j < J_SK) { convert_job(p.sk, (bf16_t*)(p.ws + OFF_SK), j); continue; }
;     j -= J_SK;
;     if (j < J_U) { convert_i8_job(p.u, (unsigned char*)(p.ws + OFF_U), j, UI8_SCALE); continue; }
;     j -= J_U;
;     convert8_job(p.v, (unsigned char*)(p.ws + OFF_V), j, 128.f);
.LBB0_26:
	s_cmpk_gt_u32 s46, 0x3bf
	s_cbranch_scc0 .LBB0_52
	s_cmpk_gt_u32 s46, 0x4bf
	s_cbranch_scc0 .LBB0_41
	s_cmpk_gt_u32 s46, 0x6bf
	s_cbranch_scc0 .LBB0_38
	s_cmpk_gt_u32 s46, 0x6df
	s_cbranch_scc0 .LBB0_35
	v_lshlrev_b32_e32 v56, 6, v118
	v_bfe_u32 v0, v118, 3, 3
	v_lshlrev_b32_e32 v57, 21, v0
	v_lshrrev_b32_e32 v0, 6, v118
	v_lshl_or_b32 v57, v0, 7, v57
	v_and_b32_e32 v0, 7, v118
	v_lshl_or_b32 v57, v0, 4, v57
	v_mov_b32_e32 v58, 0xffffff81
	v_mov_b32_e32 v59, 0x7f
	s_mov_b32 s4, s46
	s_cmp_lt_u32 s4, 0xee0
	s_cselect_b32 s6, s62, s64
	s_cselect_b32 s7, s63, s65
	s_cselect_b32 s8, s70, s68
	s_cselect_b32 s9, s71, s69
	s_sub_i32 s13, s4, 0x6e0
	s_and_b32 s13, s13, 0x7ff
	s_lshl_b32 s14, s13, 15
	s_lshl_b32 s13, s13, 10
	s_add_u32 s6, s6, s14
	s_addc_u32 s7, s7, 0
	s_add_u32 s8, s8, s13
	s_addc_u32 s9, s9, 0
	global_load_dwordx4 v[184:187], v56, s[6:7]
	global_load_dwordx4 v[188:191], v56, s[6:7] offset:16
	global_load_dwordx4 v[192:195], v56, s[6:7] offset:32
	global_load_dwordx4 v[196:199], v56, s[6:7] offset:48
	s_add_u32 s6, s6, 0x4000
	s_addc_u32 s7, s7, 0
	global_load_dwordx4 v[200:203], v56, s[6:7]
	global_load_dwordx4 v[204:207], v56, s[6:7] offset:16
	global_load_dwordx4 v[208:211], v56, s[6:7] offset:32
	global_load_dwordx4 v[212:215], v56, s[6:7] offset:48
	s_mov_b32 s12, 1
.Lpp_loop:
	s_add_i32 s5, s4, s94
	s_cmp_lt_u32 s5, 0x16e0
	s_cbranch_scc0 .Lpp_last_a
	s_cmp_lt_u32 s5, 0xee0
	s_cselect_b32 s6, s62, s64
	s_cselect_b32 s7, s63, s65
	s_cselect_b32 s10, s70, s68
	s_cselect_b32 s11, s71, s69
	s_sub_i32 s13, s5, 0x6e0
	s_and_b32 s13, s13, 0x7ff
	s_lshl_b32 s14, s13, 15
	s_lshl_b32 s13, s13, 10
	s_add_u32 s6, s6, s14
	s_addc_u32 s7, s7, 0
	s_add_u32 s10, s10, s13
	s_addc_u32 s11, s11, 0
	global_load_dwordx4 v[216:219], v56, s[6:7]
	global_load_dwordx4 v[220:223], v56, s[6:7] offset:16
	global_load_dwordx4 v[224:227], v56, s[6:7] offset:32
	global_load_dwordx4 v[228:231], v56, s[6:7] offset:48
	s_add_u32 s6, s6, 0x4000
	s_addc_u32 s7, s7, 0
	global_load_dwordx4 v[232:235], v56, s[6:7]
	global_load_dwordx4 v[236:239], v56, s[6:7] offset:16
	global_load_dwordx4 v[240:243], v56, s[6:7] offset:32
	global_load_dwordx4 v[244:247], v56, s[6:7] offset:48
	s_cmp_eq_u32 s12, 1
	s_cbranch_scc1 .Lpp_first_a
	s_waitcnt vmcnt(10)
	s_branch .Lpp_go_a
.Lpp_first_a:
	s_waitcnt vmcnt(8)
	s_mov_b32 s12, 0
.Lpp_go_a:
	s_cmp_lt_u32 s4, 0xee0
	s_cbranch_scc0 .Lpp_f8_a
	v_mul_f32_e32 v184, 0x44400000, v184
	v_mul_f32_e32 v185, 0x44400000, v185
	v_mul_f32_e32 v186, 0x44400000, v186
	v_mul_f32_e32 v187, 0x44400000, v187
	v_mul_f32_e32 v188, 0x44400000, v188
	v_mul_f32_e32 v189, 0x44400000, v189
	v_mul_f32_e32 v190, 0x44400000, v190
	v_mul_f32_e32 v191, 0x44400000, v191
	v_mul_f32_e32 v192, 0x44400000, v192
	v_mul_f32_e32 v193, 0x44400000, v193
	v_mul_f32_e32 v194, 0x44400000, v194
	v_mul_f32_e32 v195, 0x44400000, v195
	v_mul_f32_e32 v196, 0x44400000, v196
	v_mul_f32_e32 v197, 0x44400000, v197
	v_mul_f32_e32 v198, 0x44400000, v198
	v_mul_f32_e32 v199, 0x44400000, v199
	v_rndne_f32_e32 v184, v184
	v_rndne_f32_e32 v185, v185
	v_rndne_f32_e32 v186, v186
	v_rndne_f32_e32 v187, v187
	v_rndne_f32_e32 v188, v188
	v_rndne_f32_e32 v189, v189
	v_rndne_f32_e32 v190, v190
	v_rndne_f32_e32 v191, v191
	v_rndne_f32_e32 v192, v192
	v_rndne_f32_e32 v193, v193
	v_rndne_f32_e32 v194, v194
	v_rndne_f32_e32 v195, v195
	v_rndne_f32_e32 v196, v196
	v_rndne_f32_e32 v197, v197
	v_rndne_f32_e32 v198, v198
	v_rndne_f32_e32 v199, v199
	v_cvt_i32_f32_e32 v184, v184
	v_cvt_i32_f32_e32 v185, v185
	v_cvt_i32_f32_e32 v186, v186
	v_cvt_i32_f32_e32 v187, v187
	v_cvt_i32_f32_e32 v188, v188
	v_cvt_i32_f32_e32 v189, v189
	v_cvt_i32_f32_e32 v190, v190
	v_cvt_i32_f32_e32 v191, v191
	v_cvt_i32_f32_e32 v192, v192
	v_cvt_i32_f32_e32 v193, v193
	v_cvt_i32_f32_e32 v194, v194
	v_cvt_i32_f32_e32 v195, v195
	v_cvt_i32_f32_e32 v196, v196
	v_cvt_i32_f32_e32 v197, v197
	v_cvt_i32_f32_e32 v198, v198
	v_cvt_i32_f32_e32 v199, v199
	v_med3_i32 v184, v184, v58, v59
	v_med3_i32 v185, v185, v58, v59
	v_med3_i32 v186, v186, v58, v59
	v_med3_i32 v187, v187, v58, v59
	v_med3_i32 v188, v188, v58, v59
	v_med3_i32 v189, v189, v58, v59
	v_med3_i32 v190, v190, v58, v59
	v_med3_i32 v191, v191, v58, v59
	v_med3_i32 v192, v192, v58, v59
	v_med3_i32 v193, v193, v58, v59
	v_med3_i32 v194, v194, v58, v59
	v_med3_i32 v195, v195, v58, v59
	v_med3_i32 v196, v196, v58, v59
	v_med3_i32 v197, v197, v58, v59
	v_med3_i32 v198, v198, v58, v59
	v_med3_i32 v199, v199, v58, v59
	v_and_b32_e32 v184, 0xff, v184
	v_and_b32_e32 v185, 0xff, v185
	v_and_b32_e32 v186, 0xff, v186
	v_lshl_or_b32 v184, v185, 8, v184
	v_lshl_or_b32 v184, v186, 16, v184
	v_lshl_or_b32 v60, v187, 24, v184
	v_and_b32_e32 v188, 0xff, v188
	v_and_b32_e32 v189, 0xff, v189
	v_and_b32_e32 v190, 0xff, v190
	v_lshl_or_b32 v188, v189, 8, v188
	v_lshl_or_b32 v188, v190, 16, v188
	v_lshl_or_b32 v61, v191, 24, v188
	v_and_b32_e32 v192, 0xff, v192
	v_and_b32_e32 v193, 0xff, v193
	v_and_b32_e32 v194, 0xff, v194
	v_lshl_or_b32 v192, v193, 8, v192
	v_lshl_or_b32 v192, v194, 16, v192
	v_lshl_or_b32 v62, v195, 24, v192
	v_and_b32_e32 v196, 0xff, v196
	v_and_b32_e32 v197, 0xff, v197
	v_and_b32_e32 v198, 0xff, v198
	v_lshl_or_b32 v196, v197, 8, v196
	v_lshl_or_b32 v196, v198, 16, v196
	v_lshl_or_b32 v63, v199, 24, v196
	global_store_dwordx4 v57, v[60:63], s[8:9]
	s_nop 1
	v_mul_f32_e32 v200, 0x44400000, v200
	v_mul_f32_e32 v201, 0x44400000, v201
	v_mul_f32_e32 v202, 0x44400000, v202
	v_mul_f32_e32 v203, 0x44400000, v203
	v_mul_f32_e32 v204, 0x44400000, v204
	v_mul_f32_e32 v205, 0x44400000, v205
	v_mul_f32_e32 v206, 0x44400000, v206
	v_mul_f32_e32 v207, 0x44400000, v207
; DI int otid() { int t; asm volatile("v_mov_b32 %0, %1" : "=v"(t) : "v"((int)threadIdx.x)); return t; }
; DI void convert8_job(const float* __restrict__ src, unsigned char* __restrict__ dst, int job, float scale) {
;   const int tid = otid();
; #pragma unroll
;   for (int i = 0; i < 2; ++i) {
;     size_t e = (size_t)job * 8192 + (size_t)(i * 256 + tid) * 16;
;     unsigned o[4];
; #pragma unroll
;     for (int q = 0; q < 4; ++q) {
;       float4 a = *(const float4*)(src + e + 4 * q);
;       int pk = __builtin_amdgcn_cvt_pk_fp8_f32(a.x * scale, a.y * scale, 0, false);
;       pk = __builtin_amdgcn_cvt_pk_fp8_f32(a.z * scale, a.w * scale, pk, true);
;       o[q] = (unsigned)pk;
;     }
;     const size_t row = e >> 10; const int col = (int)(e & 1023);
;     *(uint4*)(dst + (size_t)(col >> 7) * ((size_t)NEXP * 128) + row * 128 + (col & 127)) = make_uint4(o[0], o[1], o[2], o[3]);
;   }
; }
; DI void convert_i8_job(const float* __restrict__ src, unsigned char* __restrict__ dst, int job, float scale) {
;   const int tid = otid();
; #pragma unroll
;   for (int i = 0; i < 2; ++i) {
;     size_t e = (size_t)job * 8192 + (size_t)(i * 256 + tid) * 16;
;     unsigned o[4];
; #pragma unroll
;     for (int q = 0; q < 4; ++q) {
;       float4 a = *(const float4*)(src + e + 4 * q);
;       o[q] = pack_i8x4(a.x, a.y, a.z, a.w, scale);
;     }
;     const size_t row = e >> 10; const int col = (int)(e & 1023);
;     *(uint4*)(dst + (size_t)(col >> 7) * ((size_t)NEXP * 128) + row * 128 + (col & 127)) = make_uint4(o[0], o[1], o[2], o[3]);
;   }
; }
	v_mul_f32_e32 v208, 0x44400000, v208
	v_mul_f32_e32 v209, 0x44400000, v209
	v_mul_f32_e32 v210, 0x44400000, v210
	v_mul_f32_e32 v211, 0x44400000, v211
	v_mul_f32_e32 v212, 0x44400000, v212
	v_mul_f32_e32 v213, 0x44400000, v213
	v_mul_f32_e32 v214, 0x44400000, v214
	v_mul_f32_e32 v215, 0x44400000, v215
	v_rndne_f32_e32 v200, v200
	v_rndne_f32_e32 v201, v201
	v_rndne_f32_e32 v202, v202
	v_rndne_f32_e32 v203, v203
	v_rndne_f32_e32 v204, v204
	v_rndne_f32_e32 v205, v205
	v_rndne_f32_e32 v206, v206
	v_rndne_f32_e32 v207, v207
	v_rndne_f32_e32 v208, v208
	v_rndne_f32_e32 v209, v209
	v_rndne_f32_e32 v210, v210
	v_rndne_f32_e32 v211, v211
	v_rndne_f32_e32 v212, v212
	v_rndne_f32_e32 v213, v213
	v_rndne_f32_e32 v214, v214
	v_rndne_f32_e32 v215, v215
	v_cvt_i32_f32_e32 v200, v200
	v_cvt_i32_f32_e32 v201, v201
	v_cvt_i32_f32_e32 v202, v202
	v_cvt_i32_f32_e32 v203, v203
	v_cvt_i32_f32_e32 v204, v204
	v_cvt_i32_f32_e32 v205, v205
	v_cvt_i32_f32_e32 v206, v206
	v_cvt_i32_f32_e32 v207, v207
	v_cvt_i32_f32_e32 v208, v208
	v_cvt_i32_f32_e32 v209, v209
	v_cvt_i32_f32_e32 v210, v210
	v_cvt_i32_f32_e32 v211, v211
	v_cvt_i32_f32_e32 v212, v212
	v_cvt_i32_f32_e32 v213, v213
	v_cvt_i32_f32_e32 v214, v214
	v_cvt_i32_f32_e32 v215, v215
	v_med3_i32 v200, v200, v58, v59
	v_med3_i32 v201, v201, v58, v59
	v_med3_i32 v202, v202, v58, v59
	v_med3_i32 v203, v203, v58, v59
	v_med3_i32 v204, v204, v58, v59
	v_med3_i32 v205, v205, v58, v59
	v_med3_i32 v206, v206, v58, v59
	v_med3_i32 v207, v207, v58, v59
	v_med3_i32 v208, v208, v58, v59
	v_med3_i32 v209, v209, v58, v59
	v_med3_i32 v210, v210, v58, v59
	v_med3_i32 v211, v211, v58, v59
	v_med3_i32 v212, v212, v58, v59
	v_med3_i32 v213, v213, v58, v59
	v_med3_i32 v214, v214, v58, v59
	v_med3_i32 v215, v215, v58, v59
	v_and_b32_e32 v200, 0xff, v200
	v_and_b32_e32 v201, 0xff, v201
	v_and_b32_e32 v202, 0xff, v202
	v_lshl_or_b32 v200, v201, 8, v200
	v_lshl_or_b32 v200, v202, 16, v200
	v_lshl_or_b32 v60, v203, 24, v200
	v_and_b32_e32 v204, 0xff, v204
	v_and_b32_e32 v205, 0xff, v205
	v_and_b32_e32 v206, 0xff, v206
	v_lshl_or_b32 v204, v205, 8, v204
	v_lshl_or_b32 v204, v206, 16, v204
	v_lshl_or_b32 v61, v207, 24, v204
	v_and_b32_e32 v208, 0xff, v208
	v_and_b32_e32 v209, 0xff, v209
	v_and_b32_e32 v210, 0xff, v210
	v_lshl_or_b32 v208, v209, 8, v208
	v_lshl_or_b32 v208, v210, 16, v208
	v_lshl_or_b32 v62, v211, 24, v208
	v_and_b32_e32 v212, 0xff, v212
	v_and_b32_e32 v213, 0xff, v213
	v_and_b32_e32 v214, 0xff, v214
	v_lshl_or_b32 v212, v213, 8, v212
	v_lshl_or_b32 v212, v214, 16, v212
	v_lshl_or_b32 v63, v215, 24, v212
	global_store_dwordx4 v57, v[60:63], s[8:9] offset:512
	s_branch .Lpp_cd_a
.Lpp_f8_a:
	v_mul_f32_e32 v184, 0x43000000, v184
	v_mul_f32_e32 v185, 0x43000000, v185
	v_mul_f32_e32 v186, 0x43000000, v186
	v_mul_f32_e32 v187, 0x43000000, v187
	v_mul_f32_e32 v188, 0x43000000, v188
	v_mul_f32_e32 v189, 0x43000000, v189
	v_mul_f32_e32 v190, 0x43000000, v190
	v_mul_f32_e32 v191, 0x43000000, v191
	v_mul_f32_e32 v192, 0x43000000, v192
	v_mul_f32_e32 v193, 0x43000000, v193
	v_mul_f32_e32 v194, 0x43000000, v194
	v_mul_f32_e32 v195, 0x43000000, v195
	v_mul_f32_e32 v196, 0x43000000, v196
	v_mul_f32_e32 v197, 0x43000000, v197
	v_mul_f32_e32 v198, 0x43000000, v198
	v_mul_f32_e32 v199, 0x43000000, v199
	v_mov_b32_e32 v60, 0
	v_mov_b32_e32 v61, 0
	v_mov_b32_e32 v62, 0
	v_mov_b32_e32 v63, 0
	v_cvt_pk_fp8_f32 v60, v184, v185
	v_cvt_pk_fp8_f32 v61, v188, v189
	v_cvt_pk_fp8_f32 v62, v192, v193
	v_cvt_pk_fp8_f32 v63, v196, v197
	v_cvt_pk_fp8_f32 v60, v186, v187 op_sel:[0,0,1]
	v_cvt_pk_fp8_f32 v61, v190, v191 op_sel:[0,0,1]
	v_cvt_pk_fp8_f32 v62, v194, v195 op_sel:[0,0,1]
	v_cvt_pk_fp8_f32 v63, v198, v199 op_sel:[0,0,1]
	s_nop 1
	global_store_dwordx4 v57, v[60:63], s[8:9]
	s_nop 1
	v_mul_f32_e32 v200, 0x43000000, v200
	v_mul_f32_e32 v201, 0x43000000, v201
	v_mul_f32_e32 v202, 0x43000000, v202
	v_mul_f32_e32 v203, 0x43000000, v203
	v_mul_f32_e32 v204, 0x43000000, v204
	v_mul_f32_e32 v205, 0x43000000, v205
	v_mul_f32_e32 v206, 0x43000000, v206
	v_mul_f32_e32 v207, 0x43000000, v207
	v_mul_f32_e32 v208, 0x43000000, v208
	v_mul_f32_e32 v209, 0x43000000, v209
	v_mul_f32_e32 v210, 0x43000000, v210
	v_mul_f32_e32 v211, 0x43000000, v211
	v_mul_f32_e32 v212, 0x43000000, v212
	v_mul_f32_e32 v213, 0x43000000, v213
	v_mul_f32_e32 v214, 0x43000000, v214
	v_mul_f32_e32 v215, 0x43000000, v215
	v_mov_b32_e32 v60, 0
	v_mov_b32_e32 v61, 0
	v_mov_b32_e32 v62, 0
	v_mov_b32_e32 v63, 0
	v_cvt_pk_fp8_f32 v60, v200, v201
	v_cvt_pk_fp8_f32 v61, v204, v205
	v_cvt_pk_fp8_f32 v62, v208, v209
	v_cvt_pk_fp8_f32 v63, v212, v213
	v_cvt_pk_fp8_f32 v60, v202, v203 op_sel:[0,0,1]
	v_cvt_pk_fp8_f32 v61, v206, v207 op_sel:[0,0,1]
	v_cvt_pk_fp8_f32 v62, v210, v211 op_sel:[0,0,1]
	v_cvt_pk_fp8_f32 v63, v214, v215 op_sel:[0,0,1]
	s_nop 1
	global_store_dwordx4 v57, v[60:63], s[8:9] offset:512
.Lpp_cd_a:
	s_mov_b32 s4, s5
	s_add_i32 s5, s4, s94
	s_cmp_lt_u32 s5, 0x16e0
	s_cbranch_scc0 .Lpp_last_b
	s_cmp_lt_u32 s5, 0xee0
	s_cselect_b32 s6, s62, s64
	s_cselect_b32 s7, s63, s65
	s_cselect_b32 s8, s70, s68
	s_cselect_b32 s9, s71, s69
	s_sub_i32 s13, s5, 0x6e0
	s_and_b32 s13, s13, 0x7ff
	s_lshl_b32 s14, s13, 15
	s_lshl_b32 s13, s13, 10
	s_add_u32 s6, s6, s14
	s_addc_u32 s7, s7, 0
	s_add_u32 s8, s8, s13
	s_addc_u32 s9, s9, 0
	global_load_dwordx4 v[184:187], v56, s[6:7]
	global_load_dwordx4 v[188:191], v56, s[6:7] offset:16
	global_load_dwordx4 v[192:195], v56, s[6:7] offset:32
	global_load_dwordx4 v[196:199], v56, s[6:7] offset:48
	s_add_u32 s6, s6, 0x4000
	s_addc_u32 s7, s7, 0
	global_load_dwordx4 v[200:203], v56, s[6:7]
	global_load_dwordx4 v[204:207], v56, s[6:7] offset:16
	global_load_dwordx4 v[208:211], v56, s[6:7] offset:32
	global_load_dwordx4 v[212:215], v56, s[6:7] offset:48
	s_cmp_eq_u32 s12, 1
	s_cbranch_scc1 .Lpp_first_b
	s_waitcnt vmcnt(10)
	s_branch .Lpp_go_b

; DI int otid() { int t; asm volatile("v_mov_b32 %0, %1" : "=v"(t) : "v"((int)threadIdx.x)); return t; }
; DI void convert_i8_job(const float* __restrict__ src, unsigned char* __restrict__ dst, int job, float scale) {
;   const int tid = otid();
; #pragma unroll
;   for (int i = 0; i < 2; ++i) {
;     size_t e = (size_t)job * 8192 + (size_t)(i * 256 + tid) * 16;
;     unsigned o[4];
; #pragma unroll
;     for (int q = 0; q < 4; ++q) {
;       float4 a = *(const float4*)(src + e + 4 * q);
;       o[q] = pack_i8x4(a.x, a.y, a.z, a.w, scale);
;     }
;     const size_t row = e >> 10; const int col = (int)(e & 1023);
;     *(uint4*)(dst + (size_t)(col >> 7) * ((size_t)NEXP * 128) + row * 128 + (col & 127)) = make_uint4(o[0], o[1], o[2], o[3]);
;   }
; }
.Lpp_go_b:
	s_cmp_lt_u32 s4, 0xee0
	s_cbranch_scc0 .Lpp_f8_b
	v_mul_f32_e32 v216, 0x44400000, v216
	v_mul_f32_e32 v217, 0x44400000, v217
	v_mul_f32_e32 v218, 0x44400000, v218
	v_mul_f32_e32 v219, 0x44400000, v219
	v_mul_f32_e32 v220, 0x44400000, v220
	v_mul_f32_e32 v221, 0x44400000, v221
	v_mul_f32_e32 v222, 0x44400000, v222
	v_mul_f32_e32 v223, 0x44400000, v223
	v_mul_f32_e32 v224, 0x44400000, v224
	v_mul_f32_e32 v225, 0x44400000, v225
	v_mul_f32_e32 v226, 0x44400000, v226
	v_mul_f32_e32 v227, 0x44400000, v227
	v_mul_f32_e32 v228, 0x44400000, v228
	v_mul_f32_e32 v229, 0x44400000, v229
	v_mul_f32_e32 v230, 0x44400000, v230
	v_mul_f32_e32 v231, 0x44400000, v231
	v_rndne_f32_e32 v216, v216
	v_rndne_f32_e32 v217, v217
	v_rndne_f32_e32 v218, v218
	v_rndne_f32_e32 v219, v219
	v_rndne_f32_e32 v220, v220
	v_rndne_f32_e32 v221, v221
	v_rndne_f32_e32 v222, v222
	v_rndne_f32_e32 v223, v223
	v_rndne_f32_e32 v224, v224
	v_rndne_f32_e32 v225, v225
	v_rndne_f32_e32 v226, v226
	v_rndne_f32_e32 v227, v227
	v_rndne_f32_e32 v228, v228
	v_rndne_f32_e32 v229, v229
	v_rndne_f32_e32 v230, v230
	v_rndne_f32_e32 v231, v231
	v_cvt_i32_f32_e32 v216, v216
	v_cvt_i32_f32_e32 v217, v217
	v_cvt_i32_f32_e32 v218, v218
	v_cvt_i32_f32_e32 v219, v219
	v_cvt_i32_f32_e32 v220, v220
	v_cvt_i32_f32_e32 v221, v221
	v_cvt_i32_f32_e32 v222, v222
	v_cvt_i32_f32_e32 v223, v223
	v_cvt_i32_f32_e32 v224, v224
	v_cvt_i32_f32_e32 v225, v225
	v_cvt_i32_f32_e32 v226, v226
	v_cvt_i32_f32_e32 v227, v227
	v_cvt_i32_f32_e32 v228, v228
	v_cvt_i32_f32_e32 v229, v229
	v_cvt_i32_f32_e32 v230, v230
	v_cvt_i32_f32_e32 v231, v231
	v_med3_i32 v216, v216, v58, v59
	v_med3_i32 v217, v217, v58, v59
	v_med3_i32 v218, v218, v58, v59
	v_med3_i32 v219, v219, v58, v59
	v_med3_i32 v220, v220, v58, v59
	v_med3_i32 v221, v221, v58, v59
	v_med3_i32 v222, v222, v58, v59
	v_med3_i32 v223, v223, v58, v59
	v_med3_i32 v224, v224, v58, v59
	v_med3_i32 v225, v225, v58, v59
	v_med3_i32 v226, v226, v58, v59
	v_med3_i32 v227, v227, v58, v59
	v_med3_i32 v228, v228, v58, v59
	v_med3_i32 v229, v229, v58, v59
	v_med3_i32 v230, v230, v58, v59
	v_med3_i32 v231, v231, v58, v59
	v_and_b32_e32 v216, 0xff, v216
	v_and_b32_e32 v217, 0xff, v217
	v_and_b32_e32 v218, 0xff, v218
	v_lshl_or_b32 v216, v217, 8, v216
	v_lshl_or_b32 v216, v218, 16, v216
	v_lshl_or_b32 v60, v219, 24, v216
	v_and_b32_e32 v220, 0xff, v220
	v_and_b32_e32 v221, 0xff, v221
	v_and_b32_e32 v222, 0xff, v222
	v_lshl_or_b32 v220, v221, 8, v220
	v_lshl_or_b32 v220, v222, 16, v220
	v_lshl_or_b32 v61, v223, 24, v220
	v_and_b32_e32 v224, 0xff, v224
	v_and_b32_e32 v225, 0xff, v225
	v_and_b32_e32 v226, 0xff, v226
	v_lshl_or_b32 v224, v225, 8, v224
	v_lshl_or_b32 v224, v226, 16, v224
	v_lshl_or_b32 v62, v227, 24, v224
	v_and_b32_e32 v228, 0xff, v228
	v_and_b32_e32 v229, 0xff, v229
	v_and_b32_e32 v230, 0xff, v230
	v_lshl_or_b32 v228, v229, 8, v228
	v_lshl_or_b32 v228, v230, 16, v228
	v_lshl_or_b32 v63, v231, 24, v228
	global_store_dwordx4 v57, v[60:63], s[10:11]
	s_nop 1
	v_mul_f32_e32 v232, 0x44400000, v232
	v_mul_f32_e32 v233, 0x44400000, v233
	v_mul_f32_e32 v234, 0x44400000, v234
	v_mul_f32_e32 v235, 0x44400000, v235
	v_mul_f32_e32 v236, 0x44400000, v236
	v_mul_f32_e32 v237, 0x44400000, v237
	v_mul_f32_e32 v238, 0x44400000, v238
	v_mul_f32_e32 v239, 0x44400000, v239
	v_mul_f32_e32 v240, 0x44400000, v240
	v_mul_f32_e32 v241, 0x44400000, v241
	v_mul_f32_e32 v242, 0x44400000, v242
	v_mul_f32_e32 v243, 0x44400000, v243
	v_mul_f32_e32 v244, 0x44400000, v244
	v_mul_f32_e32 v245, 0x44400000, v245
	v_mul_f32_e32 v246, 0x44400000, v246
	v_mul_f32_e32 v247, 0x44400000, v247
	v_rndne_f32_e32 v232, v232
	v_rndne_f32_e32 v233, v233
	v_rndne_f32_e32 v234, v234
	v_rndne_f32_e32 v235, v235
	v_rndne_f32_e32 v236, v236
	v_rndne_f32_e32 v237, v237
	v_rndne_f32_e32 v238, v238
	v_rndne_f32_e32 v239, v239
	v_rndne_f32_e32 v240, v240
	v_rndne_f32_e32 v241, v241
	v_rndne_f32_e32 v242, v242
	v_rndne_f32_e32 v243, v243
	v_rndne_f32_e32 v244, v244
	v_rndne_f32_e32 v245, v245
	v_rndne_f32_e32 v246, v246
	v_rndne_f32_e32 v247, v247
	v_cvt_i32_f32_e32 v232, v232
	v_cvt_i32_f32_e32 v233, v233
	v_cvt_i32_f32_e32 v234, v234
	v_cvt_i32_f32_e32 v235, v235
	v_cvt_i32_f32_e32 v236, v236
	v_cvt_i32_f32_e32 v237, v237
	v_cvt_i32_f32_e32 v238, v238
	v_cvt_i32_f32_e32 v239, v239
	v_cvt_i32_f32_e32 v240, v240
	v_cvt_i32_f32_e32 v241, v241
	v_cvt_i32_f32_e32 v242, v242
	v_cvt_i32_f32_e32 v243, v243
	v_cvt_i32_f32_e32 v244, v244
	v_cvt_i32_f32_e32 v245, v245
	v_cvt_i32_f32_e32 v246, v246
	v_cvt_i32_f32_e32 v247, v247
	v_med3_i32 v232, v232, v58, v59
	v_med3_i32 v233, v233, v58, v59
	v_med3_i32 v234, v234, v58, v59
	v_med3_i32 v235, v235, v58, v59
	v_med3_i32 v236, v236, v58, v59
	v_med3_i32 v237, v237, v58, v59
	v_med3_i32 v238, v238, v58, v59
	v_med3_i32 v239, v239, v58, v59
	v_med3_i32 v240, v240, v58, v59
	v_med3_i32 v241, v241, v58, v59
	v_med3_i32 v242, v242, v58, v59
	v_med3_i32 v243, v243, v58, v59
	v_med3_i32 v244, v244, v58, v59
	v_med3_i32 v245, v245, v58, v59
	v_med3_i32 v246, v246, v58, v59
	v_med3_i32 v247, v247, v58, v59
	v_and_b32_e32 v232, 0xff, v232
	v_and_b32_e32 v233, 0xff, v233
	v_and_b32_e32 v234, 0xff, v234
	v_lshl_or_b32 v232, v233, 8, v232
	v_lshl_or_b32 v232, v234, 16, v232
	v_lshl_or_b32 v60, v235, 24, v232
	v_and_b32_e32 v236, 0xff, v236
	v_and_b32_e32 v237, 0xff, v237
	v_and_b32_e32 v238, 0xff, v238
	v_lshl_or_b32 v236, v237, 8, v236
	v_lshl_or_b32 v236, v238, 16, v236
	v_lshl_or_b32 v61, v239, 24, v236
	v_and_b32_e32 v240, 0xff, v240
	v_and_b32_e32 v241, 0xff, v241
	v_and_b32_e32 v242, 0xff, v242
	v_lshl_or_b32 v240, v241, 8, v240
	v_lshl_or_b32 v240, v242, 16, v240
	v_lshl_or_b32 v62, v243, 24, v240
	v_and_b32_e32 v244, 0xff, v244
	v_and_b32_e32 v245, 0xff, v245
	v_and_b32_e32 v246, 0xff, v246
	v_lshl_or_b32 v244, v245, 8, v244
	v_lshl_or_b32 v244, v246, 16, v244
	v_lshl_or_b32 v63, v247, 24, v244
	global_store_dwordx4 v57, v[60:63], s[10:11] offset:512
	s_branch .Lpp_cd_b
; DI int otid() { int t; asm volatile("v_mov_b32 %0, %1" : "=v"(t) : "v"((int)threadIdx.x)); return t; }
; DI void convert8_job(const float* __restrict__ src, unsigned char* __restrict__ dst, int job, float scale) {
;   const int tid = otid();
; #pragma unroll
;   for (int i = 0; i < 2; ++i) {
;     size_t e = (size_t)job * 8192 + (size_t)(i * 256 + tid) * 16;
;     unsigned o[4];
; #pragma unroll
;     for (int q = 0; q < 4; ++q) {
;       float4 a = *(const float4*)(src + e + 4 * q);
;       int pk = __builtin_amdgcn_cvt_pk_fp8_f32(a.x * scale, a.y * scale, 0, false);
;       pk = __builtin_amdgcn_cvt_pk_fp8_f32(a.z * scale, a.w * scale, pk, true);
;       o[q] = (unsigned)pk;
;     }
;     const size_t row = e >> 10; const int col = (int)(e & 1023);
;     *(uint4*)(dst + (size_t)(col >> 7) * ((size_t)NEXP * 128) + row * 128 + (col & 127)) = make_uint4(o[0], o[1], o[2], o[3]);
;   }
; }
.Lpp_f8_b:
	v_mul_f32_e32 v216, 0x43000000, v216
	v_mul_f32_e32 v217, 0x43000000, v217
	v_mul_f32_e32 v218, 0x43000000, v218
	v_mul_f32_e32 v219, 0x43000000, v219
	v_mul_f32_e32 v220, 0x43000000, v220
	v_mul_f32_e32 v221, 0x43000000, v221
	v_mul_f32_e32 v222, 0x43000000, v222
	v_mul_f32_e32 v223, 0x43000000, v223
	v_mul_f32_e32 v224, 0x43000000, v224
	v_mul_f32_e32 v225, 0x43000000, v225
	v_mul_f32_e32 v226, 0x43000000, v226
	v_mul_f32_e32 v227, 0x43000000, v227
	v_mul_f32_e32 v228, 0x43000000, v228
	v_mul_f32_e32 v229, 0x43000000, v229
	v_mul_f32_e32 v230, 0x43000000, v230
	v_mul_f32_e32 v231, 0x43000000, v231
	v_mov_b32_e32 v60, 0
	v_mov_b32_e32 v61, 0
	v_mov_b32_e32 v62, 0
	v_mov_b32_e32 v63, 0
	v_cvt_pk_fp8_f32 v60, v216, v217
	v_cvt_pk_fp8_f32 v61, v220, v221
	v_cvt_pk_fp8_f32 v62, v224, v225
	v_cvt_pk_fp8_f32 v63, v228, v229
	v_cvt_pk_fp8_f32 v60, v218, v219 op_sel:[0,0,1]
	v_cvt_pk_fp8_f32 v61, v222, v223 op_sel:[0,0,1]
	v_cvt_pk_fp8_f32 v62, v226, v227 op_sel:[0,0,1]
	v_cvt_pk_fp8_f32 v63, v230, v231 op_sel:[0,0,1]
	s_nop 1
	global_store_dwordx4 v57, v[60:63], s[10:11]
	s_nop 1
	v_mul_f32_e32 v232, 0x43000000, v232
	v_mul_f32_e32 v233, 0x43000000, v233
	v_mul_f32_e32 v234, 0x43000000, v234
	v_mul_f32_e32 v235, 0x43000000, v235
	v_mul_f32_e32 v236, 0x43000000, v236
	v_mul_f32_e32 v237, 0x43000000, v237
	v_mul_f32_e32 v238, 0x43000000, v238
	v_mul_f32_e32 v239, 0x43000000, v239
	v_mul_f32_e32 v240, 0x43000000, v240
	v_mul_f32_e32 v241, 0x43000000, v241
	v_mul_f32_e32 v242, 0x43000000, v242
	v_mul_f32_e32 v243, 0x43000000, v243
	v_mul_f32_e32 v244, 0x43000000, v244
	v_mul_f32_e32 v245, 0x43000000, v245
	v_mul_f32_e32 v246, 0x43000000, v246
	v_mul_f32_e32 v247, 0x43000000, v247
	v_mov_b32_e32 v60, 0
	v_mov_b32_e32 v61, 0
	v_mov_b32_e32 v62, 0
	v_mov_b32_e32 v63, 0
	v_cvt_pk_fp8_f32 v60, v232, v233
	v_cvt_pk_fp8_f32 v61, v236, v237
	v_cvt_pk_fp8_f32 v62, v240, v241
	v_cvt_pk_fp8_f32 v63, v244, v245
	v_cvt_pk_fp8_f32 v60, v234, v235 op_sel:[0,0,1]
	v_cvt_pk_fp8_f32 v61, v238, v239 op_sel:[0,0,1]
	v_cvt_pk_fp8_f32 v62, v242, v243 op_sel:[0,0,1]
	v_cvt_pk_fp8_f32 v63, v246, v247 op_sel:[0,0,1]
	s_nop 1
	global_store_dwordx4 v57, v[60:63], s[10:11] offset:512
.Lpp_cd_b:
	s_mov_b32 s4, s5
	s_branch .Lpp_loop
; DI int otid() { int t; asm volatile("v_mov_b32 %0, %1" : "=v"(t) : "v"((int)threadIdx.x)); return t; }
; DI void convert_i8_job(const float* __restrict__ src, unsigned char* __restrict__ dst, int job, float scale) {
;   const int tid = otid();
; #pragma unroll
;   for (int i = 0; i < 2; ++i) {
;     size_t e = (size_t)job * 8192 + (size_t)(i * 256 + tid) * 16;
;     unsigned o[4];
; #pragma unroll
;     for (int q = 0; q < 4; ++q) {
;       float4 a = *(const float4*)(src + e + 4 * q);
;       o[q] = pack_i8x4(a.x, a.y, a.z, a.w, scale);
;     }
;     const size_t row = e >> 10; const int col = (int)(e & 1023);
;     *(uint4*)(dst + (size_t)(col >> 7) * ((size_t)NEXP * 128) + row * 128 + (col & 127)) = make_uint4(o[0], o[1], o[2], o[3]);
;   }
; }
.Lpp_last_a:
	s_waitcnt vmcnt(0)
	s_cmp_lt_u32 s4, 0xee0
	s_cbranch_scc0 .Lpp_f8_la
	v_mul_f32_e32 v184, 0x44400000, v184
	v_mul_f32_e32 v185, 0x44400000, v185
	v_mul_f32_e32 v186, 0x44400000, v186
	v_mul_f32_e32 v187, 0x44400000, v187
	v_mul_f32_e32 v188, 0x44400000, v188
	v_mul_f32_e32 v189, 0x44400000, v189
	v_mul_f32_e32 v190, 0x44400000, v190
	v_mul_f32_e32 v191, 0x44400000, v191
	v_mul_f32_e32 v192, 0x44400000, v192
	v_mul_f32_e32 v193, 0x44400000, v193
	v_mul_f32_e32 v194, 0x44400000, v194
	v_mul_f32_e32 v195, 0x44400000, v195
	v_mul_f32_e32 v196, 0x44400000, v196
	v_mul_f32_e32 v197, 0x44400000, v197
	v_mul_f32_e32 v198, 0x44400000, v198
	v_mul_f32_e32 v199, 0x44400000, v199
	v_rndne_f32_e32 v184, v184
	v_rndne_f32_e32 v185, v185
	v_rndne_f32_e32 v186, v186
	v_rndne_f32_e32 v187, v187
	v_rndne_f32_e32 v188, v188
	v_rndne_f32_e32 v189, v189
	v_rndne_f32_e32 v190, v190
	v_rndne_f32_e32 v191, v191
	v_rndne_f32_e32 v192, v192
	v_rndne_f32_e32 v193, v193
	v_rndne_f32_e32 v194, v194
	v_rndne_f32_e32 v195, v195
	v_rndne_f32_e32 v196, v196
	v_rndne_f32_e32 v197, v197
	v_rndne_f32_e32 v198, v198
	v_rndne_f32_e32 v199, v199
	v_cvt_i32_f32_e32 v184, v184
	v_cvt_i32_f32_e32 v185, v185
	v_cvt_i32_f32_e32 v186, v186
	v_cvt_i32_f32_e32 v187, v187
	v_cvt_i32_f32_e32 v188, v188
	v_cvt_i32_f32_e32 v189, v189
	v_cvt_i32_f32_e32 v190, v190
	v_cvt_i32_f32_e32 v191, v191
	v_cvt_i32_f32_e32 v192, v192
	v_cvt_i32_f32_e32 v193, v193
	v_cvt_i32_f32_e32 v194, v194
	v_cvt_i32_f32_e32 v195, v195
	v_cvt_i32_f32_e32 v196, v196
	v_cvt_i32_f32_e32 v197, v197
	v_cvt_i32_f32_e32 v198, v198
	v_cvt_i32_f32_e32 v199, v199
	v_med3_i32 v184, v184, v58, v59
	v_med3_i32 v185, v185, v58, v59
	v_med3_i32 v186, v186, v58, v59
	v_med3_i32 v187, v187, v58, v59
	v_med3_i32 v188, v188, v58, v59
	v_med3_i32 v189, v189, v58, v59
	v_med3_i32 v190, v190, v58, v59
	v_med3_i32 v191, v191, v58, v59
	v_med3_i32 v192, v192, v58, v59
	v_med3_i32 v193, v193, v58, v59
	v_med3_i32 v194, v194, v58, v59
	v_med3_i32 v195, v195, v58, v59
	v_med3_i32 v196, v196, v58, v59
	v_med3_i32 v197, v197, v58, v59
	v_med3_i32 v198, v198, v58, v59
	v_med3_i32 v199, v199, v58, v59
	v_and_b32_e32 v184, 0xff, v184
	v_and_b32_e32 v185, 0xff, v185
	v_and_b32_e32 v186, 0xff, v186
	v_lshl_or_b32 v184, v185, 8, v184
	v_lshl_or_b32 v184, v186, 16, v184
	v_lshl_or_b32 v60, v187, 24, v184
	v_and_b32_e32 v188, 0xff, v188
	v_and_b32_e32 v189, 0xff, v189
	v_and_b32_e32 v190, 0xff, v190
	v_lshl_or_b32 v188, v189, 8, v188
	v_lshl_or_b32 v188, v190, 16, v188
	v_lshl_or_b32 v61, v191, 24, v188
	v_and_b32_e32 v192, 0xff, v192
	v_and_b32_e32 v193, 0xff, v193
	v_and_b32_e32 v194, 0xff, v194
	v_lshl_or_b32 v192, v193, 8, v192
	v_lshl_or_b32 v192, v194, 16, v192
	v_lshl_or_b32 v62, v195, 24, v192
	v_and_b32_e32 v196, 0xff, v196
	v_and_b32_e32 v197, 0xff, v197
	v_and_b32_e32 v198, 0xff, v198
	v_lshl_or_b32 v196, v197, 8, v196
	v_lshl_or_b32 v196, v198, 16, v196
	v_lshl_or_b32 v63, v199, 24, v196
	global_store_dwordx4 v57, v[60:63], s[8:9]
	s_nop 1
	v_mul_f32_e32 v200, 0x44400000, v200
	v_mul_f32_e32 v201, 0x44400000, v201
	v_mul_f32_e32 v202, 0x44400000, v202
	v_mul_f32_e32 v203, 0x44400000, v203
	v_mul_f32_e32 v204, 0x44400000, v204
	v_mul_f32_e32 v205, 0x44400000, v205
	v_mul_f32_e32 v206, 0x44400000, v206
	v_mul_f32_e32 v207, 0x44400000, v207
	v_mul_f32_e32 v208, 0x44400000, v208
	v_mul_f32_e32 v209, 0x44400000, v209
	v_mul_f32_e32 v210, 0x44400000, v210
	v_mul_f32_e32 v211, 0x44400000, v211
	v_mul_f32_e32 v212, 0x44400000, v212
	v_mul_f32_e32 v213, 0x44400000, v213
	v_mul_f32_e32 v214, 0x44400000, v214
	v_mul_f32_e32 v215, 0x44400000, v215
	v_rndne_f32_e32 v200, v200
	v_rndne_f32_e32 v201, v201
	v_rndne_f32_e32 v202, v202
	v_rndne_f32_e32 v203, v203
	v_rndne_f32_e32 v204, v204
	v_rndne_f32_e32 v205, v205
	v_rndne_f32_e32 v206, v206
	v_rndne_f32_e32 v207, v207
	v_rndne_f32_e32 v208, v208
	v_rndne_f32_e32 v209, v209
	v_rndne_f32_e32 v210, v210
	v_rndne_f32_e32 v211, v211
	v_rndne_f32_e32 v212, v212
	v_rndne_f32_e32 v213, v213
	v_rndne_f32_e32 v214, v214
	v_rndne_f32_e32 v215, v215
	v_cvt_i32_f32_e32 v200, v200
	v_cvt_i32_f32_e32 v201, v201
	v_cvt_i32_f32_e32 v202, v202
	v_cvt_i32_f32_e32 v203, v203
	v_cvt_i32_f32_e32 v204, v204
	v_cvt_i32_f32_e32 v205, v205
	v_cvt_i32_f32_e32 v206, v206
	v_cvt_i32_f32_e32 v207, v207
	v_cvt_i32_f32_e32 v208, v208
	v_cvt_i32_f32_e32 v209, v209
	v_cvt_i32_f32_e32 v210, v210
	v_cvt_i32_f32_e32 v211, v211
	v_cvt_i32_f32_e32 v212, v212
	v_cvt_i32_f32_e32 v213, v213
	v_cvt_i32_f32_e32 v214, v214
	v_cvt_i32_f32_e32 v215, v215
	v_med3_i32 v200, v200, v58, v59
	v_med3_i32 v201, v201, v58, v59
	v_med3_i32 v202, v202, v58, v59
	v_med3_i32 v203, v203, v58, v59
	v_med3_i32 v204, v204, v58, v59
	v_med3_i32 v205, v205, v58, v59
	v_med3_i32 v206, v206, v58, v59
	v_med3_i32 v207, v207, v58, v59
	v_med3_i32 v208, v208, v58, v59
	v_med3_i32 v209, v209, v58, v59
	v_med3_i32 v210, v210, v58, v59
	v_med3_i32 v211, v211, v58, v59
	v_med3_i32 v212, v212, v58, v59
	v_med3_i32 v213, v213, v58, v59
	v_med3_i32 v214, v214, v58, v59
	v_med3_i32 v215, v215, v58, v59
	v_and_b32_e32 v200, 0xff, v200
	v_and_b32_e32 v201, 0xff, v201
	v_and_b32_e32 v202, 0xff, v202
	v_lshl_or_b32 v200, v201, 8, v200
	v_lshl_or_b32 v200, v202, 16, v200
	v_lshl_or_b32 v60, v203, 24, v200
	v_and_b32_e32 v204, 0xff, v204
	v_and_b32_e32 v205, 0xff, v205
	v_and_b32_e32 v206, 0xff, v206
	v_lshl_or_b32 v204, v205, 8, v204
	v_lshl_or_b32 v204, v206, 16, v204
	v_lshl_or_b32 v61, v207, 24, v204
	v_and_b32_e32 v208, 0xff, v208
	v_and_b32_e32 v209, 0xff, v209
	v_and_b32_e32 v210, 0xff, v210
	v_lshl_or_b32 v208, v209, 8, v208
	v_lshl_or_b32 v208, v210, 16, v208
	v_lshl_or_b32 v62, v211, 24, v208
	v_and_b32_e32 v212, 0xff, v212
	v_and_b32_e32 v213, 0xff, v213
	v_and_b32_e32 v214, 0xff, v214
	v_lshl_or_b32 v212, v213, 8, v212
	v_lshl_or_b32 v212, v214, 16, v212
	v_lshl_or_b32 v63, v215, 24, v212
	global_store_dwordx4 v57, v[60:63], s[8:9] offset:512
	s_branch .Lpp_cd_la

; DI int otid() { int t; asm volatile("v_mov_b32 %0, %1" : "=v"(t) : "v"((int)threadIdx.x)); return t; }
; DI void convert_i8_job(const float* __restrict__ src, unsigned char* __restrict__ dst, int job, float scale) {
;   const int tid = otid();
; #pragma unroll
;   for (int i = 0; i < 2; ++i) {
;     size_t e = (size_t)job * 8192 + (size_t)(i * 256 + tid) * 16;
;     unsigned o[4];
; #pragma unroll
;     for (int q = 0; q < 4; ++q) {
;       float4 a = *(const float4*)(src + e + 4 * q);
;       o[q] = pack_i8x4(a.x, a.y, a.z, a.w, scale);
;     }
;     const size_t row = e >> 10; const int col = (int)(e & 1023);
;     *(uint4*)(dst + (size_t)(col >> 7) * ((size_t)NEXP * 128) + row * 128 + (col & 127)) = make_uint4(o[0], o[1], o[2], o[3]);
;   }
; }
.Lpp_cd_la:
	s_branch .LBB0_59
.Lpp_last_b:
	s_waitcnt vmcnt(0)
	s_cmp_lt_u32 s4, 0xee0
	s_cbranch_scc0 .Lpp_f8_lb
	v_mul_f32_e32 v216, 0x44400000, v216
	v_mul_f32_e32 v217, 0x44400000, v217
	v_mul_f32_e32 v218, 0x44400000, v218
	v_mul_f32_e32 v219, 0x44400000, v219
	v_mul_f32_e32 v220, 0x44400000, v220
	v_mul_f32_e32 v221, 0x44400000, v221
	v_mul_f32_e32 v222, 0x44400000, v222
	v_mul_f32_e32 v223, 0x44400000, v223
	v_mul_f32_e32 v224, 0x44400000, v224
	v_mul_f32_e32 v225, 0x44400000, v225
	v_mul_f32_e32 v226, 0x44400000, v226
	v_mul_f32_e32 v227, 0x44400000, v227
	v_mul_f32_e32 v228, 0x44400000, v228
	v_mul_f32_e32 v229, 0x44400000, v229
	v_mul_f32_e32 v230, 0x44400000, v230
	v_mul_f32_e32 v231, 0x44400000, v231
	v_rndne_f32_e32 v216, v216
	v_rndne_f32_e32 v217, v217
	v_rndne_f32_e32 v218, v218
	v_rndne_f32_e32 v219, v219
	v_rndne_f32_e32 v220, v220
	v_rndne_f32_e32 v221, v221
	v_rndne_f32_e32 v222, v222
	v_rndne_f32_e32 v223, v223
	v_rndne_f32_e32 v224, v224
	v_rndne_f32_e32 v225, v225
	v_rndne_f32_e32 v226, v226
	v_rndne_f32_e32 v227, v227
	v_rndne_f32_e32 v228, v228
	v_rndne_f32_e32 v229, v229
	v_rndne_f32_e32 v230, v230
	v_rndne_f32_e32 v231, v231
	v_cvt_i32_f32_e32 v216, v216
	v_cvt_i32_f32_e32 v217, v217
	v_cvt_i32_f32_e32 v218, v218
	v_cvt_i32_f32_e32 v219, v219
	v_cvt_i32_f32_e32 v220, v220
	v_cvt_i32_f32_e32 v221, v221
	v_cvt_i32_f32_e32 v222, v222
	v_cvt_i32_f32_e32 v223, v223
	v_cvt_i32_f32_e32 v224, v224
	v_cvt_i32_f32_e32 v225, v225
	v_cvt_i32_f32_e32 v226, v226
	v_cvt_i32_f32_e32 v227, v227
	v_cvt_i32_f32_e32 v228, v228
	v_cvt_i32_f32_e32 v229, v229
	v_cvt_i32_f32_e32 v230, v230
	v_cvt_i32_f32_e32 v231, v231
	v_med3_i32 v216, v216, v58, v59
	v_med3_i32 v217, v217, v58, v59
	v_med3_i32 v218, v218, v58, v59
	v_med3_i32 v219, v219, v58, v59
	v_med3_i32 v220, v220, v58, v59
	v_med3_i32 v221, v221, v58, v59
	v_med3_i32 v222, v222, v58, v59
	v_med3_i32 v223, v223, v58, v59
	v_med3_i32 v224, v224, v58, v59
	v_med3_i32 v225, v225, v58, v59
	v_med3_i32 v226, v226, v58, v59
	v_med3_i32 v227, v227, v58, v59
	v_med3_i32 v228, v228, v58, v59
	v_med3_i32 v229, v229, v58, v59
	v_med3_i32 v230, v230, v58, v59
	v_med3_i32 v231, v231, v58, v59
	v_and_b32_e32 v216, 0xff, v216
	v_and_b32_e32 v217, 0xff, v217
	v_and_b32_e32 v218, 0xff, v218
	v_lshl_or_b32 v216, v217, 8, v216
	v_lshl_or_b32 v216, v218, 16, v216
	v_lshl_or_b32 v60, v219, 24, v216
	v_and_b32_e32 v220, 0xff, v220
	v_and_b32_e32 v221, 0xff, v221
	v_and_b32_e32 v222, 0xff, v222
	v_lshl_or_b32 v220, v221, 8, v220
	v_lshl_or_b32 v220, v222, 16, v220
	v_lshl_or_b32 v61, v223, 24, v220
	v_and_b32_e32 v224, 0xff, v224
	v_and_b32_e32 v225, 0xff, v225
	v_and_b32_e32 v226, 0xff, v226
	v_lshl_or_b32 v224, v225, 8, v224
	v_lshl_or_b32 v224, v226, 16, v224
	v_lshl_or_b32 v62, v227, 24, v224
	v_and_b32_e32 v228, 0xff, v228
	v_and_b32_e32 v229, 0xff, v229
	v_and_b32_e32 v230, 0xff, v230
	v_lshl_or_b32 v228, v229, 8, v228
	v_lshl_or_b32 v228, v230, 16, v228
	v_lshl_or_b32 v63, v231, 24, v228
	global_store_dwordx4 v57, v[60:63], s[10:11]
	s_nop 1
	v_mul_f32_e32 v232, 0x44400000, v232
	v_mul_f32_e32 v233, 0x44400000, v233
	v_mul_f32_e32 v234, 0x44400000, v234
	v_mul_f32_e32 v235, 0x44400000, v235
	v_mul_f32_e32 v236, 0x44400000, v236
	v_mul_f32_e32 v237, 0x44400000, v237
	v_mul_f32_e32 v238, 0x44400000, v238
	v_mul_f32_e32 v239, 0x44400000, v239
	v_mul_f32_e32 v240, 0x44400000, v240
	v_mul_f32_e32 v241, 0x44400000, v241
	v_mul_f32_e32 v242, 0x44400000, v242
	v_mul_f32_e32 v243, 0x44400000, v243
	v_mul_f32_e32 v244, 0x44400000, v244
	v_mul_f32_e32 v245, 0x44400000, v245
	v_mul_f32_e32 v246, 0x44400000, v246
	v_mul_f32_e32 v247, 0x44400000, v247
	v_rndne_f32_e32 v232, v232
	v_rndne_f32_e32 v233, v233
	v_rndne_f32_e32 v234, v234
	v_rndne_f32_e32 v235, v235
	v_rndne_f32_e32 v236, v236
	v_rndne_f32_e32 v237, v237
	v_rndne_f32_e32 v238, v238
	v_rndne_f32_e32 v239, v239
	v_rndne_f32_e32 v240, v240
	v_rndne_f32_e32 v241, v241
	v_rndne_f32_e32 v242, v242
	v_rndne_f32_e32 v243, v243
	v_rndne_f32_e32 v244, v244
	v_rndne_f32_e32 v245, v245
	v_rndne_f32_e32 v246, v246
	v_rndne_f32_e32 v247, v247
	v_cvt_i32_f32_e32 v232, v232
	v_cvt_i32_f32_e32 v233, v233
	v_cvt_i32_f32_e32 v234, v234
	v_cvt_i32_f32_e32 v235, v235
	v_cvt_i32_f32_e32 v236, v236
	v_cvt_i32_f32_e32 v237, v237
	v_cvt_i32_f32_e32 v238, v238
	v_cvt_i32_f32_e32 v239, v239
	v_cvt_i32_f32_e32 v240, v240
	v_cvt_i32_f32_e32 v241, v241
	v_cvt_i32_f32_e32 v242, v242
	v_cvt_i32_f32_e32 v243, v243
	v_cvt_i32_f32_e32 v244, v244
	v_cvt_i32_f32_e32 v245, v245
	v_cvt_i32_f32_e32 v246, v246
	v_cvt_i32_f32_e32 v247, v247
	v_med3_i32 v232, v232, v58, v59
	v_med3_i32 v233, v233, v58, v59
	v_med3_i32 v234, v234, v58, v59
	v_med3_i32 v235, v235, v58, v59
	v_med3_i32 v236, v236, v58, v59
	v_med3_i32 v237, v237, v58, v59
	v_med3_i32 v238, v238, v58, v59
	v_med3_i32 v239, v239, v58, v59
	v_med3_i32 v240, v240, v58, v59
	v_med3_i32 v241, v241, v58, v59
	v_med3_i32 v242, v242, v58, v59
	v_med3_i32 v243, v243, v58, v59
	v_med3_i32 v244, v244, v58, v59
	v_med3_i32 v245, v245, v58, v59
	v_med3_i32 v246, v246, v58, v59
	v_med3_i32 v247, v247, v58, v59
	v_and_b32_e32 v232, 0xff, v232
	v_and_b32_e32 v233, 0xff, v233
	v_and_b32_e32 v234, 0xff, v234
	v_lshl_or_b32 v232, v233, 8, v232
	v_lshl_or_b32 v232, v234, 16, v232
	v_lshl_or_b32 v60, v235, 24, v232
	v_and_b32_e32 v236, 0xff, v236
	v_and_b32_e32 v237, 0xff, v237
	v_and_b32_e32 v238, 0xff, v238
	v_lshl_or_b32 v236, v237, 8, v236
	v_lshl_or_b32 v236, v238, 16, v236
	v_lshl_or_b32 v61, v239, 24, v236
	v_and_b32_e32 v240, 0xff, v240
	v_and_b32_e32 v241, 0xff, v241
	v_and_b32_e32 v242, 0xff, v242
	v_lshl_or_b32 v240, v241, 8, v240
	v_lshl_or_b32 v240, v242, 16, v240
	v_lshl_or_b32 v62, v243, 24, v240
	v_and_b32_e32 v244, 0xff, v244
	v_and_b32_e32 v245, 0xff, v245
	v_and_b32_e32 v246, 0xff, v246
	v_lshl_or_b32 v244, v245, 8, v244
	v_lshl_or_b32 v244, v246, 16, v244
	v_lshl_or_b32 v63, v247, 24, v244
	global_store_dwordx4 v57, v[60:63], s[10:11] offset:512
	s_branch .Lpp_cd_lb
